# lnfold stack + write-through (sc0 sc1) stores in the FFN-up SwiGLU epilogue so that the following grid barrier's L2 writeback finds little dirty data
# baseline (speedup 1.0000x reference)
.LBB0_170:
	v_lshl_or_b32 v150, s34, 7, v146
	v_lshl_add_u32 v148, s36, 8, v144
	v_ashrrev_i32_e32 v151, 31, v150
	v_mov_b64_e32 v[142:143], s[20:21]
	s_andn2_b64 vcc, exec, s[4:5]
	s_movk_i32 s65, 0xff5d
	s_movk_i32 s64, 0xff7c
	v_lshlrev_b64 v[152:153], 1, v[150:151]
	v_add_u32_e32 v192, 0, v148
	v_mul_f32_e32 v156, 0xbfb8aa3b, v126
	v_mul_f32_e32 v157, 0xbfb8aa3b, v127
	v_mul_f32_e32 v158, 0xbfb8aa3b, v128
	v_mul_f32_e32 v159, 0xbfb8aa3b, v129
	v_mul_f32_e32 v160, 0xbfb8aa3b, v118
	v_mul_f32_e32 v161, 0xbfb8aa3b, v119
	v_mul_f32_e32 v162, 0xbfb8aa3b, v120
	v_mul_f32_e32 v163, 0xbfb8aa3b, v121
	v_mad_i64_i32 v[188:189], s[34:35], v192, s47, v[142:143]
	v_exp_f32_e32 v156, v156
	v_exp_f32_e32 v157, v157
	v_exp_f32_e32 v158, v158
	v_exp_f32_e32 v159, v159
	v_exp_f32_e32 v160, v160
	v_exp_f32_e32 v161, v161
	v_exp_f32_e32 v162, v162
	v_exp_f32_e32 v163, v163
	v_lshl_add_u64 v[188:189], v[188:189], 0, v[152:153]
	v_add_f32_e32 v156, 1.0, v156
	v_add_f32_e32 v157, 1.0, v157
	v_add_f32_e32 v158, 1.0, v158
	v_add_f32_e32 v159, 1.0, v159
	v_add_f32_e32 v160, 1.0, v160
	v_add_f32_e32 v161, 1.0, v161
	v_add_f32_e32 v162, 1.0, v162
	v_add_f32_e32 v163, 1.0, v163
	v_rcp_f32_e32 v156, v156
	v_rcp_f32_e32 v157, v157
	v_rcp_f32_e32 v158, v158
	v_rcp_f32_e32 v159, v159
	v_rcp_f32_e32 v160, v160
	v_rcp_f32_e32 v161, v161
	v_rcp_f32_e32 v162, v162
	v_rcp_f32_e32 v163, v163
	v_mul_f32_e32 v156, v126, v156
	v_mul_f32_e32 v157, v127, v157
	v_mul_f32_e32 v158, v128, v158
	v_mul_f32_e32 v159, v129, v159
	v_mul_f32_e32 v160, v118, v160
	v_mul_f32_e32 v161, v119, v161
	v_mul_f32_e32 v162, v120, v162
	v_mul_f32_e32 v163, v121, v163
	v_mul_f32_e32 v156, v156, v122
	v_mul_f32_e32 v157, v157, v123
	v_mul_f32_e32 v158, v158, v124
	v_mul_f32_e32 v159, v159, v125
	v_mul_f32_e32 v160, v160, v114
	v_mul_f32_e32 v161, v161, v115
	v_mul_f32_e32 v162, v162, v116
	v_mul_f32_e32 v163, v163, v117
	v_cvt_pk_bf16_f32 v180, v156, v157
	v_cvt_pk_bf16_f32 v181, v158, v159
	v_cvt_pk_bf16_f32 v182, v160, v161
	v_cvt_pk_bf16_f32 v183, v162, v163
	global_store_dwordx4 v[188:189], v[180:183], off sc0 sc1
	v_add_u32_e32 v193, 16, v148
	v_mul_f32_e32 v164, 0xbfb8aa3b, v110
	v_mul_f32_e32 v165, 0xbfb8aa3b, v111
	v_mul_f32_e32 v166, 0xbfb8aa3b, v112
	v_mul_f32_e32 v167, 0xbfb8aa3b, v113
	v_mul_f32_e32 v168, 0xbfb8aa3b, v102
	v_mul_f32_e32 v169, 0xbfb8aa3b, v103
	v_mul_f32_e32 v170, 0xbfb8aa3b, v104
	v_mul_f32_e32 v171, 0xbfb8aa3b, v105
	v_mad_i64_i32 v[190:191], s[34:35], v193, s47, v[142:143]
	v_exp_f32_e32 v164, v164
	v_exp_f32_e32 v165, v165
	v_exp_f32_e32 v166, v166
	v_exp_f32_e32 v167, v167
	v_exp_f32_e32 v168, v168
	v_exp_f32_e32 v169, v169
	v_exp_f32_e32 v170, v170
	v_exp_f32_e32 v171, v171
	v_lshl_add_u64 v[190:191], v[190:191], 0, v[152:153]
	v_add_f32_e32 v164, 1.0, v164
	v_add_f32_e32 v165, 1.0, v165
	v_add_f32_e32 v166, 1.0, v166
	v_add_f32_e32 v167, 1.0, v167
	v_add_f32_e32 v168, 1.0, v168
	v_add_f32_e32 v169, 1.0, v169
	v_add_f32_e32 v170, 1.0, v170
	v_add_f32_e32 v171, 1.0, v171
	v_rcp_f32_e32 v164, v164
	v_rcp_f32_e32 v165, v165
	v_rcp_f32_e32 v166, v166
	v_rcp_f32_e32 v167, v167
	v_rcp_f32_e32 v168, v168
	v_rcp_f32_e32 v169, v169
	v_rcp_f32_e32 v170, v170
	v_rcp_f32_e32 v171, v171
	v_mul_f32_e32 v164, v110, v164
	v_mul_f32_e32 v165, v111, v165
	v_mul_f32_e32 v166, v112, v166
	v_mul_f32_e32 v167, v113, v167
	v_mul_f32_e32 v168, v102, v168
	v_mul_f32_e32 v169, v103, v169
	v_mul_f32_e32 v170, v104, v170
	v_mul_f32_e32 v171, v105, v171
	v_mul_f32_e32 v164, v164, v106
	v_mul_f32_e32 v165, v165, v107
	v_mul_f32_e32 v166, v166, v108
	v_mul_f32_e32 v167, v167, v109
	v_mul_f32_e32 v168, v168, v98
	v_mul_f32_e32 v169, v169, v99
	v_mul_f32_e32 v170, v170, v100
	v_mul_f32_e32 v171, v171, v101
	v_cvt_pk_bf16_f32 v184, v164, v165
	v_cvt_pk_bf16_f32 v185, v166, v167
	v_cvt_pk_bf16_f32 v186, v168, v169
	v_cvt_pk_bf16_f32 v187, v170, v171
	global_store_dwordx4 v[190:191], v[184:187], off sc0 sc1
	v_add_u32_e32 v192, 32, v148
	v_mul_f32_e32 v156, 0xbfb8aa3b, v94
	v_mul_f32_e32 v157, 0xbfb8aa3b, v95
	v_mul_f32_e32 v158, 0xbfb8aa3b, v96
	v_mul_f32_e32 v159, 0xbfb8aa3b, v97
	v_mul_f32_e32 v160, 0xbfb8aa3b, v86
	v_mul_f32_e32 v161, 0xbfb8aa3b, v87
	v_mul_f32_e32 v162, 0xbfb8aa3b, v88
	v_mul_f32_e32 v163, 0xbfb8aa3b, v89
	v_mad_i64_i32 v[188:189], s[34:35], v192, s47, v[142:143]
	v_exp_f32_e32 v156, v156
	v_exp_f32_e32 v157, v157
	v_exp_f32_e32 v158, v158
	v_exp_f32_e32 v159, v159
	v_exp_f32_e32 v160, v160
	v_exp_f32_e32 v161, v161
	v_exp_f32_e32 v162, v162
	v_exp_f32_e32 v163, v163
	v_lshl_add_u64 v[188:189], v[188:189], 0, v[152:153]
	v_add_f32_e32 v156, 1.0, v156
	v_add_f32_e32 v157, 1.0, v157
	v_add_f32_e32 v158, 1.0, v158
	v_add_f32_e32 v159, 1.0, v159
	v_add_f32_e32 v160, 1.0, v160
	v_add_f32_e32 v161, 1.0, v161
	v_add_f32_e32 v162, 1.0, v162
	v_add_f32_e32 v163, 1.0, v163
	v_rcp_f32_e32 v156, v156
	v_rcp_f32_e32 v157, v157
	v_rcp_f32_e32 v158, v158
	v_rcp_f32_e32 v159, v159
	v_rcp_f32_e32 v160, v160
	v_rcp_f32_e32 v161, v161
	v_rcp_f32_e32 v162, v162
	v_rcp_f32_e32 v163, v163
	v_mul_f32_e32 v156, v94, v156
	v_mul_f32_e32 v157, v95, v157
	v_mul_f32_e32 v158, v96, v158
	v_mul_f32_e32 v159, v97, v159
	v_mul_f32_e32 v160, v86, v160
	v_mul_f32_e32 v161, v87, v161
	v_mul_f32_e32 v162, v88, v162
	v_mul_f32_e32 v163, v89, v163
	v_mul_f32_e32 v156, v156, v90
	v_mul_f32_e32 v157, v157, v91
	v_mul_f32_e32 v158, v158, v92
	v_mul_f32_e32 v159, v159, v93
	v_mul_f32_e32 v160, v160, v82
	v_mul_f32_e32 v161, v161, v83
	v_mul_f32_e32 v162, v162, v84
	v_mul_f32_e32 v163, v163, v85
	v_cvt_pk_bf16_f32 v180, v156, v157
	v_cvt_pk_bf16_f32 v181, v158, v159
	v_cvt_pk_bf16_f32 v182, v160, v161
	v_cvt_pk_bf16_f32 v183, v162, v163
	global_store_dwordx4 v[188:189], v[180:183], off sc0 sc1
	v_add_u32_e32 v193, 48, v148
	v_mul_f32_e32 v164, 0xbfb8aa3b, v78
	v_mul_f32_e32 v165, 0xbfb8aa3b, v79
	v_mul_f32_e32 v166, 0xbfb8aa3b, v80
	v_mul_f32_e32 v167, 0xbfb8aa3b, v81
	v_mul_f32_e32 v168, 0xbfb8aa3b, v70
	v_mul_f32_e32 v169, 0xbfb8aa3b, v71
	v_mul_f32_e32 v170, 0xbfb8aa3b, v72
	v_mul_f32_e32 v171, 0xbfb8aa3b, v73
	v_mad_i64_i32 v[190:191], s[34:35], v193, s47, v[142:143]
	v_exp_f32_e32 v164, v164
	v_exp_f32_e32 v165, v165
	v_exp_f32_e32 v166, v166
	v_exp_f32_e32 v167, v167
	v_exp_f32_e32 v168, v168
	v_exp_f32_e32 v169, v169
	v_exp_f32_e32 v170, v170
	v_exp_f32_e32 v171, v171
	v_lshl_add_u64 v[190:191], v[190:191], 0, v[152:153]
	v_add_f32_e32 v164, 1.0, v164
	v_add_f32_e32 v165, 1.0, v165
	v_add_f32_e32 v166, 1.0, v166
	v_add_f32_e32 v167, 1.0, v167
	v_add_f32_e32 v168, 1.0, v168
	v_add_f32_e32 v169, 1.0, v169
	v_add_f32_e32 v170, 1.0, v170
	v_add_f32_e32 v171, 1.0, v171
	v_rcp_f32_e32 v164, v164
	v_rcp_f32_e32 v165, v165
	v_rcp_f32_e32 v166, v166
	v_rcp_f32_e32 v167, v167
	v_rcp_f32_e32 v168, v168
	v_rcp_f32_e32 v169, v169
	v_rcp_f32_e32 v170, v170
	v_rcp_f32_e32 v171, v171
	v_mul_f32_e32 v164, v78, v164
	v_mul_f32_e32 v165, v79, v165
	v_mul_f32_e32 v166, v80, v166
	v_mul_f32_e32 v167, v81, v167
	v_mul_f32_e32 v168, v70, v168
	v_mul_f32_e32 v169, v71, v169
	v_mul_f32_e32 v170, v72, v170
	v_mul_f32_e32 v171, v73, v171
	v_mul_f32_e32 v164, v164, v74
	v_mul_f32_e32 v165, v165, v75
	v_mul_f32_e32 v166, v166, v76
	v_mul_f32_e32 v167, v167, v77
	v_mul_f32_e32 v168, v168, v66
	v_mul_f32_e32 v169, v169, v67
	v_mul_f32_e32 v170, v170, v68
	v_mul_f32_e32 v171, v171, v69
	v_cvt_pk_bf16_f32 v184, v164, v165
	v_cvt_pk_bf16_f32 v185, v166, v167
	v_cvt_pk_bf16_f32 v186, v168, v169
	v_cvt_pk_bf16_f32 v187, v170, v171
	global_store_dwordx4 v[190:191], v[184:187], off sc0 sc1
	v_add_u32_e32 v192, 0x80, v148
	v_mul_f32_e32 v156, 0xbfb8aa3b, v62
	v_mul_f32_e32 v157, 0xbfb8aa3b, v63
	v_mul_f32_e32 v158, 0xbfb8aa3b, v64
	v_mul_f32_e32 v159, 0xbfb8aa3b, v65
	v_mul_f32_e32 v160, 0xbfb8aa3b, v54
	v_mul_f32_e32 v161, 0xbfb8aa3b, v55
	v_mul_f32_e32 v162, 0xbfb8aa3b, v56
	v_mul_f32_e32 v163, 0xbfb8aa3b, v57
	v_mad_i64_i32 v[188:189], s[34:35], v192, s47, v[142:143]
	v_exp_f32_e32 v156, v156
	v_exp_f32_e32 v157, v157
	v_exp_f32_e32 v158, v158
	v_exp_f32_e32 v159, v159
	v_exp_f32_e32 v160, v160
	v_exp_f32_e32 v161, v161
	v_exp_f32_e32 v162, v162
	v_exp_f32_e32 v163, v163
	v_lshl_add_u64 v[188:189], v[188:189], 0, v[152:153]
	v_add_f32_e32 v156, 1.0, v156
	v_add_f32_e32 v157, 1.0, v157
	v_add_f32_e32 v158, 1.0, v158
	v_add_f32_e32 v159, 1.0, v159
	v_add_f32_e32 v160, 1.0, v160
	v_add_f32_e32 v161, 1.0, v161
	v_add_f32_e32 v162, 1.0, v162
	v_add_f32_e32 v163, 1.0, v163
	v_rcp_f32_e32 v156, v156
	v_rcp_f32_e32 v157, v157
	v_rcp_f32_e32 v158, v158
	v_rcp_f32_e32 v159, v159
	v_rcp_f32_e32 v160, v160
	v_rcp_f32_e32 v161, v161
	v_rcp_f32_e32 v162, v162
	v_rcp_f32_e32 v163, v163
	v_mul_f32_e32 v156, v62, v156
	v_mul_f32_e32 v157, v63, v157
	v_mul_f32_e32 v158, v64, v158
	v_mul_f32_e32 v159, v65, v159
	v_mul_f32_e32 v160, v54, v160
	v_mul_f32_e32 v161, v55, v161
	v_mul_f32_e32 v162, v56, v162
	v_mul_f32_e32 v163, v57, v163
	v_mul_f32_e32 v156, v156, v58
	v_mul_f32_e32 v157, v157, v59
	v_mul_f32_e32 v158, v158, v60
	v_mul_f32_e32 v159, v159, v61
	v_mul_f32_e32 v160, v160, v50
	v_mul_f32_e32 v161, v161, v51
	v_mul_f32_e32 v162, v162, v52
	v_mul_f32_e32 v163, v163, v53
	v_cvt_pk_bf16_f32 v180, v156, v157
	v_cvt_pk_bf16_f32 v181, v158, v159
	v_cvt_pk_bf16_f32 v182, v160, v161
	v_cvt_pk_bf16_f32 v183, v162, v163
	global_store_dwordx4 v[188:189], v[180:183], off sc0 sc1
	v_add_u32_e32 v193, 0x90, v148
	v_mul_f32_e32 v164, 0xbfb8aa3b, v46
	v_mul_f32_e32 v165, 0xbfb8aa3b, v47
	v_mul_f32_e32 v166, 0xbfb8aa3b, v48
	v_mul_f32_e32 v167, 0xbfb8aa3b, v49
	v_mul_f32_e32 v168, 0xbfb8aa3b, v38
	v_mul_f32_e32 v169, 0xbfb8aa3b, v39
	v_mul_f32_e32 v170, 0xbfb8aa3b, v40
	v_mul_f32_e32 v171, 0xbfb8aa3b, v41
	v_mad_i64_i32 v[190:191], s[34:35], v193, s47, v[142:143]
	v_exp_f32_e32 v164, v164
	v_exp_f32_e32 v165, v165
	v_exp_f32_e32 v166, v166
	v_exp_f32_e32 v167, v167
	v_exp_f32_e32 v168, v168
	v_exp_f32_e32 v169, v169
	v_exp_f32_e32 v170, v170
	v_exp_f32_e32 v171, v171
	v_lshl_add_u64 v[190:191], v[190:191], 0, v[152:153]
	v_add_f32_e32 v164, 1.0, v164
	v_add_f32_e32 v165, 1.0, v165
	v_add_f32_e32 v166, 1.0, v166
	v_add_f32_e32 v167, 1.0, v167
	v_add_f32_e32 v168, 1.0, v168
	v_add_f32_e32 v169, 1.0, v169
	v_add_f32_e32 v170, 1.0, v170
	v_add_f32_e32 v171, 1.0, v171
	v_rcp_f32_e32 v164, v164
	v_rcp_f32_e32 v165, v165
	v_rcp_f32_e32 v166, v166
	v_rcp_f32_e32 v167, v167
	v_rcp_f32_e32 v168, v168
	v_rcp_f32_e32 v169, v169
	v_rcp_f32_e32 v170, v170
	v_rcp_f32_e32 v171, v171
	v_mul_f32_e32 v164, v46, v164
	v_mul_f32_e32 v165, v47, v165
	v_mul_f32_e32 v166, v48, v166
	v_mul_f32_e32 v167, v49, v167
	v_mul_f32_e32 v168, v38, v168
	v_mul_f32_e32 v169, v39, v169
	v_mul_f32_e32 v170, v40, v170
	v_mul_f32_e32 v171, v41, v171
	v_mul_f32_e32 v164, v164, v42
	v_mul_f32_e32 v165, v165, v43
	v_mul_f32_e32 v166, v166, v44
	v_mul_f32_e32 v167, v167, v45
	v_mul_f32_e32 v168, v168, v34
	v_mul_f32_e32 v169, v169, v35
	v_mul_f32_e32 v170, v170, v36
	v_mul_f32_e32 v171, v171, v37
	v_cvt_pk_bf16_f32 v184, v164, v165
	v_cvt_pk_bf16_f32 v185, v166, v167
	v_cvt_pk_bf16_f32 v186, v168, v169
	v_cvt_pk_bf16_f32 v187, v170, v171
	global_store_dwordx4 v[190:191], v[184:187], off sc0 sc1
	v_add_u32_e32 v192, 0xa0, v148
	v_mul_f32_e32 v156, 0xbfb8aa3b, v30
	v_mul_f32_e32 v157, 0xbfb8aa3b, v31
	v_mul_f32_e32 v158, 0xbfb8aa3b, v32
	v_mul_f32_e32 v159, 0xbfb8aa3b, v33
	v_mul_f32_e32 v160, 0xbfb8aa3b, v22
	v_mul_f32_e32 v161, 0xbfb8aa3b, v23
	v_mul_f32_e32 v162, 0xbfb8aa3b, v24
	v_mul_f32_e32 v163, 0xbfb8aa3b, v25
	v_mad_i64_i32 v[188:189], s[34:35], v192, s47, v[142:143]
	v_exp_f32_e32 v156, v156
	v_exp_f32_e32 v157, v157
	v_exp_f32_e32 v158, v158
	v_exp_f32_e32 v159, v159
	v_exp_f32_e32 v160, v160
	v_exp_f32_e32 v161, v161
	v_exp_f32_e32 v162, v162
	v_exp_f32_e32 v163, v163
	v_lshl_add_u64 v[188:189], v[188:189], 0, v[152:153]
	v_add_f32_e32 v156, 1.0, v156
	v_add_f32_e32 v157, 1.0, v157
	v_add_f32_e32 v158, 1.0, v158
	v_add_f32_e32 v159, 1.0, v159
	v_add_f32_e32 v160, 1.0, v160
	v_add_f32_e32 v161, 1.0, v161
	v_add_f32_e32 v162, 1.0, v162
	v_add_f32_e32 v163, 1.0, v163
	v_rcp_f32_e32 v156, v156
	v_rcp_f32_e32 v157, v157
	v_rcp_f32_e32 v158, v158
	v_rcp_f32_e32 v159, v159
	v_rcp_f32_e32 v160, v160
	v_rcp_f32_e32 v161, v161
	v_rcp_f32_e32 v162, v162
	v_rcp_f32_e32 v163, v163
	v_mul_f32_e32 v156, v30, v156
	v_mul_f32_e32 v157, v31, v157
	v_mul_f32_e32 v158, v32, v158
	v_mul_f32_e32 v159, v33, v159
	v_mul_f32_e32 v160, v22, v160
	v_mul_f32_e32 v161, v23, v161
	v_mul_f32_e32 v162, v24, v162
	v_mul_f32_e32 v163, v25, v163
	v_mul_f32_e32 v156, v156, v26
	v_mul_f32_e32 v157, v157, v27
	v_mul_f32_e32 v158, v158, v28
	v_mul_f32_e32 v159, v159, v29
	v_mul_f32_e32 v160, v160, v18
	v_mul_f32_e32 v161, v161, v19
	v_mul_f32_e32 v162, v162, v20
	v_mul_f32_e32 v163, v163, v21
	v_cvt_pk_bf16_f32 v180, v156, v157
	v_cvt_pk_bf16_f32 v181, v158, v159
	v_cvt_pk_bf16_f32 v182, v160, v161
	v_cvt_pk_bf16_f32 v183, v162, v163
	global_store_dwordx4 v[188:189], v[180:183], off sc0 sc1
	v_add_u32_e32 v193, 0xb0, v148
	v_mul_f32_e32 v164, 0xbfb8aa3b, v14
	v_mul_f32_e32 v165, 0xbfb8aa3b, v15
	v_mul_f32_e32 v166, 0xbfb8aa3b, v16
	v_mul_f32_e32 v167, 0xbfb8aa3b, v17
	v_mul_f32_e32 v168, 0xbfb8aa3b, v6
	v_mul_f32_e32 v169, 0xbfb8aa3b, v7
	v_mul_f32_e32 v170, 0xbfb8aa3b, v8
	v_mul_f32_e32 v171, 0xbfb8aa3b, v9
	v_mad_i64_i32 v[190:191], s[34:35], v193, s47, v[142:143]
	v_exp_f32_e32 v164, v164
	v_exp_f32_e32 v165, v165
	v_exp_f32_e32 v166, v166
	v_exp_f32_e32 v167, v167
	v_exp_f32_e32 v168, v168
	v_exp_f32_e32 v169, v169
	v_exp_f32_e32 v170, v170
	v_exp_f32_e32 v171, v171
	v_lshl_add_u64 v[190:191], v[190:191], 0, v[152:153]
	v_add_f32_e32 v164, 1.0, v164
	v_add_f32_e32 v165, 1.0, v165
	v_add_f32_e32 v166, 1.0, v166
	v_add_f32_e32 v167, 1.0, v167
	v_add_f32_e32 v168, 1.0, v168
	v_add_f32_e32 v169, 1.0, v169
	v_add_f32_e32 v170, 1.0, v170
	v_add_f32_e32 v171, 1.0, v171
	v_rcp_f32_e32 v164, v164
	v_rcp_f32_e32 v165, v165
	v_rcp_f32_e32 v166, v166
	v_rcp_f32_e32 v167, v167
	v_rcp_f32_e32 v168, v168
	v_rcp_f32_e32 v169, v169
	v_rcp_f32_e32 v170, v170
	v_rcp_f32_e32 v171, v171
	v_mul_f32_e32 v164, v14, v164
	v_mul_f32_e32 v165, v15, v165
	v_mul_f32_e32 v166, v16, v166
	v_mul_f32_e32 v167, v17, v167
	v_mul_f32_e32 v168, v6, v168
	v_mul_f32_e32 v169, v7, v169
	v_mul_f32_e32 v170, v8, v170
	v_mul_f32_e32 v171, v9, v171
	v_mul_f32_e32 v164, v164, v10
	v_mul_f32_e32 v165, v165, v11
	v_mul_f32_e32 v166, v166, v12
	v_mul_f32_e32 v167, v167, v13
	v_mul_f32_e32 v168, v168, v2
	v_mul_f32_e32 v169, v169, v3
	v_mul_f32_e32 v170, v170, v4
	v_mul_f32_e32 v171, v171, v5
	v_cvt_pk_bf16_f32 v184, v164, v165
	v_cvt_pk_bf16_f32 v185, v166, v167
	v_cvt_pk_bf16_f32 v186, v168, v169
	v_cvt_pk_bf16_f32 v187, v170, v171
	global_store_dwordx4 v[190:191], v[184:187], off sc0 sc1
	s_mov_b64 s[34:35], -1
	s_cbranch_vccnz .LBB0_163
	s_andn2_b64 vcc, exec, s[12:13]
	s_cbranch_vccnz .LBB0_162
	s_barrier
	s_branch .LBB0_162
